# phase 0: dt-weight columns staged into LDS with all 32 loads per thread in flight
# speedup vs baseline: 1.0001x; 1.0001x over previous
.LBB0_453:
	s_or_b64 exec, exec, s[4:5]
	s_movk_i32 s0, 0x4000
	v_cmp_gt_i32_e32 vcc, s0, v174
	s_and_saveexec_b64 s[0:1], vcc
	s_cbranch_execz .LBB0_465
	v_readlane_b32 s2, v254, 56
	v_readlane_b32 s3, v254, 57
	s_load_dwordx2 s[2:3], s[2:3], 0x50
	v_and_b32_e32 v1, 15, v174
	v_readlane_b32 s4, v254, 11
	v_lshrrev_b32_e32 v2, 4, v174
	v_mul_u32_u24_e32 v3, 0x3840, v2
	v_lshl_add_u32 v4, v1, 12, s4
	v_lshl_add_u32 v3, v1, 2, v3
	v_lshl_add_u32 v4, v2, 2, v4
	v_add_u32_e32 v3, 0x2800, v3
	s_waitcnt lgkmcnt(0)
	global_load_dword v32, v3, s[2:3]
	s_add_u32 s2, s2, 0x70800
	s_addc_u32 s3, s3, 0
	global_load_dword v33, v3, s[2:3]
	s_add_u32 s2, s2, 0x70800
	s_addc_u32 s3, s3, 0
	global_load_dword v34, v3, s[2:3]
	s_add_u32 s2, s2, 0x70800
	s_addc_u32 s3, s3, 0
	global_load_dword v35, v3, s[2:3]
	s_add_u32 s2, s2, 0x70800
	s_addc_u32 s3, s3, 0
	global_load_dword v36, v3, s[2:3]
	s_add_u32 s2, s2, 0x70800
	s_addc_u32 s3, s3, 0
	global_load_dword v37, v3, s[2:3]
	s_add_u32 s2, s2, 0x70800
	s_addc_u32 s3, s3, 0
	global_load_dword v38, v3, s[2:3]
	s_add_u32 s2, s2, 0x70800
	s_addc_u32 s3, s3, 0
	global_load_dword v39, v3, s[2:3]
	s_add_u32 s2, s2, 0x70800
	s_addc_u32 s3, s3, 0
	global_load_dword v40, v3, s[2:3]
	s_add_u32 s2, s2, 0x70800
	s_addc_u32 s3, s3, 0
	global_load_dword v41, v3, s[2:3]
	s_add_u32 s2, s2, 0x70800
	s_addc_u32 s3, s3, 0
	global_load_dword v42, v3, s[2:3]
	s_add_u32 s2, s2, 0x70800
	s_addc_u32 s3, s3, 0
	global_load_dword v43, v3, s[2:3]
	s_add_u32 s2, s2, 0x70800
	s_addc_u32 s3, s3, 0
	global_load_dword v44, v3, s[2:3]
	s_add_u32 s2, s2, 0x70800
	s_addc_u32 s3, s3, 0
	global_load_dword v45, v3, s[2:3]
	s_add_u32 s2, s2, 0x70800
	s_addc_u32 s3, s3, 0
	global_load_dword v46, v3, s[2:3]
	s_add_u32 s2, s2, 0x70800
	s_addc_u32 s3, s3, 0
	global_load_dword v47, v3, s[2:3]
	s_add_u32 s2, s2, 0x70800
	s_addc_u32 s3, s3, 0
	global_load_dword v48, v3, s[2:3]
	s_add_u32 s2, s2, 0x70800
	s_addc_u32 s3, s3, 0
	global_load_dword v49, v3, s[2:3]
	s_add_u32 s2, s2, 0x70800
	s_addc_u32 s3, s3, 0
	global_load_dword v50, v3, s[2:3]
	s_add_u32 s2, s2, 0x70800
	s_addc_u32 s3, s3, 0
	global_load_dword v51, v3, s[2:3]
	s_add_u32 s2, s2, 0x70800
	s_addc_u32 s3, s3, 0
	global_load_dword v52, v3, s[2:3]
	s_add_u32 s2, s2, 0x70800
	s_addc_u32 s3, s3, 0
	global_load_dword v53, v3, s[2:3]
	s_add_u32 s2, s2, 0x70800
	s_addc_u32 s3, s3, 0
	global_load_dword v54, v3, s[2:3]
	s_add_u32 s2, s2, 0x70800
	s_addc_u32 s3, s3, 0
	global_load_dword v55, v3, s[2:3]
	s_add_u32 s2, s2, 0x70800
	s_addc_u32 s3, s3, 0
	global_load_dword v56, v3, s[2:3]
	s_add_u32 s2, s2, 0x70800
	s_addc_u32 s3, s3, 0
	global_load_dword v57, v3, s[2:3]
	s_add_u32 s2, s2, 0x70800
	s_addc_u32 s3, s3, 0
	global_load_dword v58, v3, s[2:3]
	s_add_u32 s2, s2, 0x70800
	s_addc_u32 s3, s3, 0
	global_load_dword v59, v3, s[2:3]
	s_add_u32 s2, s2, 0x70800
	s_addc_u32 s3, s3, 0
	global_load_dword v60, v3, s[2:3]
	s_add_u32 s2, s2, 0x70800
	s_addc_u32 s3, s3, 0
	global_load_dword v61, v3, s[2:3]
	s_add_u32 s2, s2, 0x70800
	s_addc_u32 s3, s3, 0
	global_load_dword v62, v3, s[2:3]
	s_add_u32 s2, s2, 0x70800
	s_addc_u32 s3, s3, 0
	global_load_dword v63, v3, s[2:3]
	s_waitcnt vmcnt(31)
	ds_write_b32 v4, v32
	s_waitcnt vmcnt(30)
	ds_write_b32 v4, v33 offset:128
	s_waitcnt vmcnt(29)
	ds_write_b32 v4, v34 offset:256
	s_waitcnt vmcnt(28)
	ds_write_b32 v4, v35 offset:384
	s_waitcnt vmcnt(27)
	ds_write_b32 v4, v36 offset:512
	s_waitcnt vmcnt(26)
	ds_write_b32 v4, v37 offset:640
	s_waitcnt vmcnt(25)
	ds_write_b32 v4, v38 offset:768
	s_waitcnt vmcnt(24)
	ds_write_b32 v4, v39 offset:896
	s_waitcnt vmcnt(23)
	ds_write_b32 v4, v40 offset:1024
	s_waitcnt vmcnt(22)
	ds_write_b32 v4, v41 offset:1152
	s_waitcnt vmcnt(21)
	ds_write_b32 v4, v42 offset:1280
	s_waitcnt vmcnt(20)
	ds_write_b32 v4, v43 offset:1408
	s_waitcnt vmcnt(19)
	ds_write_b32 v4, v44 offset:1536
	s_waitcnt vmcnt(18)
	ds_write_b32 v4, v45 offset:1664
	s_waitcnt vmcnt(17)
	ds_write_b32 v4, v46 offset:1792
	s_waitcnt vmcnt(16)
	ds_write_b32 v4, v47 offset:1920
	s_waitcnt vmcnt(15)
	ds_write_b32 v4, v48 offset:2048
	s_waitcnt vmcnt(14)
	ds_write_b32 v4, v49 offset:2176
	s_waitcnt vmcnt(13)
	ds_write_b32 v4, v50 offset:2304
	s_waitcnt vmcnt(12)
	ds_write_b32 v4, v51 offset:2432
	s_waitcnt vmcnt(11)
	ds_write_b32 v4, v52 offset:2560
	s_waitcnt vmcnt(10)
	ds_write_b32 v4, v53 offset:2688
	s_waitcnt vmcnt(9)
	ds_write_b32 v4, v54 offset:2816
	s_waitcnt vmcnt(8)
	ds_write_b32 v4, v55 offset:2944
	s_waitcnt vmcnt(7)
	ds_write_b32 v4, v56 offset:3072
	s_waitcnt vmcnt(6)
	ds_write_b32 v4, v57 offset:3200
	s_waitcnt vmcnt(5)
	ds_write_b32 v4, v58 offset:3328
	s_waitcnt vmcnt(4)
	ds_write_b32 v4, v59 offset:3456
	s_waitcnt vmcnt(3)
	ds_write_b32 v4, v60 offset:3584
	s_waitcnt vmcnt(2)
	ds_write_b32 v4, v61 offset:3712
	s_waitcnt vmcnt(1)
	ds_write_b32 v4, v62 offset:3840
	s_waitcnt vmcnt(0)
	ds_write_b32 v4, v63 offset:3968
